# mixer phase order split by blockIdx bit 7 (lower/upper half of each XCD's ranks)
# speedup vs baseline: 1.0037x; 1.0037x over previous
; #define LAS __attribute__((address_space(3)))
; #define LAUNDER() int tp = TID0(); const int tid = tp, lane = tp & 63, wave = __builtin_amdgcn_readfirstlane(tp >> 6); (void)tid; (void)lane; (void)wave
; __global__ void __launch_bounds__(512) fwd_kernel(Args a) {
;     ...
;         if (IN(pb + 2)) {
;             if (EN_B) { LAUNDER(); LAS char* vt = (LAS char*)lds + wave * 16384;
;                 (void)vt; for (int u = blockIdx.x; u < 256; u += G) { mixerB2_unit(u, l, PROJ, YC, a.in[6] + l * 128, a.in[7] + l * 64, KMAX + l * 1024, (LAS char*)lds, tid, wave, lane); } __syncthreads(); }
;             if (EN_S1) { LAUNDER(); __syncthreads();
;                 for (int u = blockIdx.x; u < 256; u += G) ssd_part1_unit(u, PROJ, DT, H, WDT + l * 16384, a.in[11] + l * 8, a.in[8] + l * 5 * 768, a.in[9] + l * 768, a.in[10] + l * 8, STATES, TOT, lds, tid, wave, lane);
;                 __syncthreads(); }
;             if (EN_A) { LAUNDER(); LAS char* vt = (LAS char*)lds + wave * 16384;
;                 for (int u = blockIdx.x; u < 512; u += G) { mixerA1_unit(u, PROJ, YC, LPA, KMAX + l * 1024, vt, wave, lane); } }
;             if (EN_D) { LAUNDER(); LAS char* vt = (LAS char*)lds + wave * 16384;
;                 int hcur = -1; float rmax = 0.f;
;                 for (int u = blockIdx.x; u < 512; u += G) { const int hd = (u >> 4) & 3; if (hd != hcur) { rmax = d_stage_rpb(a.in[14] + l * 4 * 15 * 31, hd, vt, lane); hcur = hd; }
;                     mixerD2_unit(u, PROJ, YC, rmax, KMAX + l * 1024, vt, wave, lane); } }
;         }
.Lmx_b:
	s_cmp_eq_u32 s101, 0
	s_cbranch_scc0 .Lmx_b_go
	s_bitcmp1_b32 s66, 7
	s_cbranch_scc0 .Lmx_b_go
	s_mov_b32 s101, 1
	v_readlane_b32 s0, v253, 56
	v_readlane_b32 s1, v253, 57
	s_nop 1
	v_cndmask_b32_e64 v6, 0, 1, s[0:1]
	s_nop 0
	v_cmp_ne_u32_e64 s[36:37], 1, v6
	s_branch .LBB0_262
